# attention: cross-half running-max exchange via v_permlane32_swap instead of ds_bpermute; V-fragment LDS wait deferred to the first PV MFMA
# baseline (speedup 1.0000x reference)
.LBB0_885:
	ds_read_b128 v[34:37], v172
	ds_read_b128 v[38:41], v172 offset:32
	ds_read_b128 v[42:45], v172 offset:64
	ds_read_b128 v[46:49], v172 offset:96
	ds_read_b128 v[98:101], v172 offset:4608
	ds_read_b128 v[102:105], v172 offset:4640
	ds_read_b128 v[106:109], v172 offset:4672
	ds_read_b128 v[110:113], v172 offset:4704
	s_waitcnt vmcnt(5) lgkmcnt(7)
	v_mfma_f32_32x32x16_bf16 v[50:65], v[34:37], v[66:69], v[206:221]
	v_add_u32_e32 v0, 0x2000, v173
	ds_read2_b64 v[126:129], v0 offset0:128 offset1:130
	ds_read2_b64 v[114:117], v0 offset0:132 offset1:134
	s_waitcnt vmcnt(4) lgkmcnt(8)
	v_mfma_f32_32x32x16_bf16 v[50:65], v[38:41], v[70:73], v[50:65]
	s_waitcnt vmcnt(1) lgkmcnt(7)
	v_mfma_f32_32x32x16_bf16 v[50:65], v[42:45], v[78:81], v[50:65]
	s_waitcnt vmcnt(0) lgkmcnt(6)
	v_mfma_f32_32x32x16_bf16 v[50:65], v[46:49], v[82:85], v[50:65]
	s_waitcnt lgkmcnt(5)
	v_mfma_f32_32x32x16_bf16 v[34:49], v[98:101], v[66:69], v[206:221]
	v_add_u32_e32 v98, 0x3000, v173
	s_waitcnt lgkmcnt(4)
	v_mfma_f32_32x32x16_bf16 v[34:49], v[102:105], v[70:73], v[34:49]
	s_waitcnt lgkmcnt(3)
	v_mfma_f32_32x32x16_bf16 v[34:49], v[106:109], v[78:81], v[34:49]
	s_waitcnt lgkmcnt(2)
	v_mfma_f32_32x32x16_bf16 v[34:49], v[110:113], v[82:85], v[34:49]
	ds_read2_b64 v[122:125], v98 offset0:160 offset1:162
	ds_read2_b64 v[118:121], v98 offset0:164 offset1:166
	ds_read2_b64 v[110:113], v0 offset0:136 offset1:138
	ds_read2_b64 v[106:109], v98 offset0:168 offset1:170
	ds_read2_b64 v[102:105], v0 offset0:140 offset1:142
	ds_read2_b64 v[98:101], v98 offset0:172 offset1:174
	v_max_f32_e32 v0, v51, v51
	v_max_f32_e32 v174, v50, v50
	v_max_f32_e32 v0, v174, v0
	v_max3_f32 v0, v0, v52, v53
	v_max3_f32 v0, v0, v54, v55
	v_max3_f32 v0, v0, v56, v57
	v_max3_f32 v0, v0, v58, v59
	v_max3_f32 v0, v0, v60, v61
	v_max3_f32 v0, v0, v62, v63
	v_max3_f32 v0, v0, v64, v65
	v_max3_f32 v0, v0, v34, v35
	v_max3_f32 v0, v0, v36, v37
	v_max3_f32 v0, v0, v38, v39
	v_max3_f32 v0, v0, v40, v41
	v_max3_f32 v0, v0, v42, v43
	v_max3_f32 v0, v0, v44, v45
	v_max3_f32 v0, v0, v46, v47
	v_max3_f32 v0, v0, v48, v49
	v_mov_b32_e32 v174, v0
	s_nop 1
	v_permlane32_swap_b32_e32 v174, v0
	s_nop 1
	v_max_f32_e32 v0, v0, v174
	v_cmp_lt_f32_e32 vcc, s98, v0
	s_cbranch_vccz .LBB0_887
	v_max_f32_e32 v174, s99, v0
	v_sub_f32_e32 v0, 0, v174
	v_min_f32_e32 v0, 0, v0
	v_exp_f32_e32 v0, v0
	v_sub_f32_e32 v206, v206, v174
	v_add_f32_e32 v151, v151, v174
	v_mov_b32_e32 v207, v206
	v_mov_b32_e32 v208, v206
	v_mov_b32_e32 v209, v206
	v_mov_b32_e32 v210, v206
	v_mov_b32_e32 v211, v206
	v_mov_b32_e32 v212, v206
	v_mov_b32_e32 v213, v206
	v_mov_b32_e32 v214, v206
	v_mov_b32_e32 v215, v206
	v_mov_b32_e32 v216, v206
	v_mov_b32_e32 v217, v206
	v_mov_b32_e32 v218, v206
	v_mov_b32_e32 v219, v206
	v_mov_b32_e32 v220, v206
	v_mov_b32_e32 v221, v206
	v_mul_f32_e32 v153, v153, v0
	v_mul_f32_e32 v32, v32, v0
	v_mul_f32_e32 v33, v33, v0
	v_mul_f32_e32 v30, v30, v0
	v_mul_f32_e32 v31, v31, v0
	v_mul_f32_e32 v28, v28, v0
	v_mul_f32_e32 v29, v29, v0
	v_mul_f32_e32 v26, v26, v0
	v_mul_f32_e32 v27, v27, v0
	v_mul_f32_e32 v24, v24, v0
	v_mul_f32_e32 v25, v25, v0
	v_mul_f32_e32 v22, v22, v0
	v_mul_f32_e32 v23, v23, v0
	v_mul_f32_e32 v20, v20, v0
	v_mul_f32_e32 v21, v21, v0
	v_mul_f32_e32 v18, v18, v0
	v_mul_f32_e32 v19, v19, v0
	v_mul_f32_e32 v16, v16, v0
	v_mul_f32_e32 v17, v17, v0
	v_mul_f32_e32 v14, v14, v0
	v_mul_f32_e32 v15, v15, v0
	v_mul_f32_e32 v12, v12, v0
	v_mul_f32_e32 v13, v13, v0
	v_mul_f32_e32 v10, v10, v0
	v_mul_f32_e32 v11, v11, v0
	v_mul_f32_e32 v8, v8, v0
	v_mul_f32_e32 v9, v9, v0
	v_mul_f32_e32 v6, v6, v0
	v_mul_f32_e32 v7, v7, v0
	v_mul_f32_e32 v4, v4, v0
	v_mul_f32_e32 v5, v5, v0
	v_mul_f32_e32 v2, v2, v0
	v_mul_f32_e32 v3, v3, v0
	v_sub_f32_e32 v50, v50, v174
	v_sub_f32_e32 v51, v51, v174
	v_sub_f32_e32 v52, v52, v174
	v_sub_f32_e32 v53, v53, v174
	v_sub_f32_e32 v54, v54, v174
	v_sub_f32_e32 v55, v55, v174
	v_sub_f32_e32 v56, v56, v174
	v_sub_f32_e32 v57, v57, v174
	v_sub_f32_e32 v58, v58, v174
	v_sub_f32_e32 v59, v59, v174
	v_sub_f32_e32 v60, v60, v174
	v_sub_f32_e32 v61, v61, v174
	v_sub_f32_e32 v62, v62, v174
	v_sub_f32_e32 v63, v63, v174
	v_sub_f32_e32 v64, v64, v174
	v_sub_f32_e32 v65, v65, v174
	v_sub_f32_e32 v34, v34, v174
	v_sub_f32_e32 v35, v35, v174
	v_sub_f32_e32 v36, v36, v174
	v_sub_f32_e32 v37, v37, v174
	v_sub_f32_e32 v38, v38, v174
	v_sub_f32_e32 v39, v39, v174
	v_sub_f32_e32 v40, v40, v174
	v_sub_f32_e32 v41, v41, v174
	v_sub_f32_e32 v42, v42, v174
	v_sub_f32_e32 v43, v43, v174
	v_sub_f32_e32 v44, v44, v174
	v_sub_f32_e32 v45, v45, v174
	v_sub_f32_e32 v46, v46, v174
	v_sub_f32_e32 v47, v47, v174
	v_sub_f32_e32 v48, v48, v174
	v_sub_f32_e32 v49, v49, v174
	s_mov_b32 s98, 0x41000000
	s_mov_b32 s99, 0
.LBB0_887:
	v_exp_f32_e32 v0, v50
	v_exp_f32_e32 v50, v51
	v_exp_f32_e32 v51, v52
	v_exp_f32_e32 v52, v53
	v_exp_f32_e32 v53, v54
	v_exp_f32_e32 v54, v55
	v_exp_f32_e32 v55, v56
	v_exp_f32_e32 v56, v57
	v_cvt_pk_bf16_f32 v174, v0, v50
	v_cvt_pk_bf16_f32 v175, v51, v52
	v_cvt_pk_bf16_f32 v176, v53, v54
	v_cvt_pk_bf16_f32 v177, v55, v56
	v_exp_f32_e32 v57, v58
	v_exp_f32_e32 v58, v59
	s_waitcnt lgkmcnt(0)
	v_mfma_f32_32x32x16_bf16 v[2:17], v[126:129], v[174:177], v[2:17]
	v_mfma_f32_32x32x16_bf16 v[18:33], v[122:125], v[174:177], v[18:33]
	v_exp_f32_e32 v59, v60
	v_exp_f32_e32 v60, v61
	v_exp_f32_e32 v61, v62
	v_exp_f32_e32 v62, v63
	v_exp_f32_e32 v63, v64
	v_exp_f32_e32 v64, v65
	v_cvt_pk_bf16_f32 v178, v57, v58
	v_cvt_pk_bf16_f32 v179, v59, v60
	v_cvt_pk_bf16_f32 v180, v61, v62
	v_cvt_pk_bf16_f32 v181, v63, v64
	v_exp_f32_e32 v34, v34
	v_exp_f32_e32 v35, v35
	v_mfma_f32_32x32x16_bf16 v[2:17], v[114:117], v[178:181], v[2:17]
	v_mfma_f32_32x32x16_bf16 v[18:33], v[118:121], v[178:181], v[18:33]
	v_exp_f32_e32 v36, v36
	v_exp_f32_e32 v37, v37
	v_exp_f32_e32 v38, v38
	v_exp_f32_e32 v39, v39
	v_exp_f32_e32 v40, v40
	v_exp_f32_e32 v41, v41
	v_cvt_pk_bf16_f32 v182, v34, v35
	v_cvt_pk_bf16_f32 v183, v36, v37
	v_cvt_pk_bf16_f32 v184, v38, v39
	v_cvt_pk_bf16_f32 v185, v40, v41
	v_exp_f32_e32 v42, v42
	v_exp_f32_e32 v43, v43
	v_mfma_f32_32x32x16_bf16 v[2:17], v[110:113], v[182:185], v[2:17]
	v_mfma_f32_32x32x16_bf16 v[18:33], v[106:109], v[182:185], v[18:33]
	v_exp_f32_e32 v44, v44
	v_exp_f32_e32 v45, v45
	v_exp_f32_e32 v46, v46
	v_exp_f32_e32 v47, v47
	v_exp_f32_e32 v48, v48
	v_exp_f32_e32 v49, v49
	v_cvt_pk_bf16_f32 v186, v42, v43
	v_cvt_pk_bf16_f32 v187, v44, v45
	v_cvt_pk_bf16_f32 v188, v46, v47
	v_cvt_pk_bf16_f32 v189, v48, v49
	s_nop 1
	v_mfma_f32_32x32x16_bf16 v[2:17], v[102:105], v[186:189], v[2:17]
	v_mfma_f32_32x32x16_bf16 v[18:33], v[98:101], v[186:189], v[18:33]
	s_movk_i32 s0, 0x6a00
	v_add3_u32 v65, v169, v132, s0
	s_cmp_gt_u32 s17, 32
	ds_write_b128 v171, v[86:89] offset:17920
	ds_write2_b64 v65, v[94:95], v[96:97] offset1:1
	s_waitcnt lgkmcnt(0)
	s_barrier
	s_cbranch_scc1 .LBB0_889
	v_add_co_u32_e32 v86, vcc, 0x1370c000, v164
	s_nop 1
	v_addc_co_u32_e32 v87, vcc, 0, v165, vcc
	v_add_co_u32_e32 v94, vcc, 0x14000000, v162
	global_load_dwordx4 v[86:89], v[86:87], off
	s_nop 0
	v_addc_co_u32_e32 v95, vcc, 0, v163, vcc
	global_load_dwordx4 v[94:97], v[94:95], off offset:384
.LBB0_889:
	v_add_f32_e32 v0, 0, v0
	v_add_f32_e32 v0, v50, v0
	v_add_f32_e32 v0, v51, v0
	v_add_f32_e32 v0, v52, v0
	v_add_f32_e32 v0, v53, v0
	v_add_f32_e32 v0, v54, v0
	v_add_f32_e32 v0, v55, v0
	v_add_f32_e32 v0, v56, v0
	v_add_f32_e32 v0, v57, v0
	v_add_f32_e32 v0, v58, v0
	v_add_f32_e32 v0, v59, v0
	v_add_f32_e32 v0, v60, v0
	v_add_f32_e32 v0, v61, v0
	v_add_f32_e32 v0, v62, v0
	v_add_f32_e32 v0, v63, v0
	v_add_f32_e32 v0, v64, v0
	v_add_f32_e32 v0, v34, v0
	v_add_f32_e32 v0, v35, v0
	v_add_f32_e32 v0, v36, v0
	v_add_f32_e32 v0, v37, v0
	v_add_f32_e32 v0, v38, v0
	v_add_f32_e32 v0, v39, v0
	v_add_f32_e32 v0, v40, v0
	v_add_f32_e32 v0, v41, v0
	v_add_f32_e32 v0, v42, v0
	v_add_f32_e32 v0, v43, v0
	v_add_f32_e32 v0, v44, v0
	v_add_f32_e32 v0, v45, v0
	v_add_f32_e32 v0, v46, v0
	v_add_f32_e32 v0, v47, v0
	v_add_f32_e32 v0, v48, v0
	v_add_f32_e32 v0, v49, v0
	ds_read_b128 v[34:37], v172 offset:17920
	ds_read_b128 v[38:41], v172 offset:17952
	ds_read_b128 v[42:45], v172 offset:17984
	ds_read_b128 v[46:49], v172 offset:18016
	ds_read_b128 v[98:101], v172 offset:22528
	ds_read_b128 v[102:105], v172 offset:22560
	ds_read_b128 v[106:109], v172 offset:22592
	ds_read_b128 v[110:113], v172 offset:22624
	v_add_f32_e32 v0, v153, v0
	s_waitcnt lgkmcnt(7)
	v_mfma_f32_32x32x16_bf16 v[50:65], v[34:37], v[66:69], v[206:221]
	s_waitcnt lgkmcnt(6)
	v_mfma_f32_32x32x16_bf16 v[50:65], v[38:41], v[70:73], v[50:65]
	s_waitcnt lgkmcnt(5)
	v_mfma_f32_32x32x16_bf16 v[50:65], v[42:45], v[78:81], v[50:65]
	s_waitcnt lgkmcnt(4)
	v_mfma_f32_32x32x16_bf16 v[50:65], v[46:49], v[82:85], v[50:65]
	s_waitcnt lgkmcnt(3)
	v_mfma_f32_32x32x16_bf16 v[34:49], v[98:101], v[66:69], v[206:221]
	v_add_u32_e32 v98, 0x6800, v173
	v_add_u32_e32 v99, 0x7800, v173
	ds_read2_b64 v[126:129], v98 offset0:64 offset1:66
	ds_read2_b64 v[114:117], v98 offset0:68 offset1:70
	s_waitcnt lgkmcnt(4)
	v_mfma_f32_32x32x16_bf16 v[34:49], v[102:105], v[70:73], v[34:49]
	s_waitcnt lgkmcnt(3)
	v_mfma_f32_32x32x16_bf16 v[34:49], v[106:109], v[78:81], v[34:49]
	s_waitcnt lgkmcnt(2)
	v_mfma_f32_32x32x16_bf16 v[34:49], v[110:113], v[82:85], v[34:49]
	ds_read2_b64 v[122:125], v99 offset0:96 offset1:98
	ds_read2_b64 v[118:121], v99 offset0:100 offset1:102
	ds_read2_b64 v[110:113], v98 offset0:72 offset1:74
	ds_read2_b64 v[106:109], v99 offset0:104 offset1:106
	ds_read2_b64 v[102:105], v98 offset0:76 offset1:78
	ds_read2_b64 v[98:101], v99 offset0:108 offset1:110
	v_max_f32_e32 v153, v51, v51
	v_max_f32_e32 v162, v50, v50
	v_max_f32_e32 v153, v162, v153
	v_max3_f32 v153, v153, v52, v53
	v_max3_f32 v153, v153, v54, v55
	v_max3_f32 v153, v153, v56, v57
	v_max3_f32 v153, v153, v58, v59
	v_max3_f32 v153, v153, v60, v61
	v_max3_f32 v153, v153, v62, v63
	v_max3_f32 v153, v153, v64, v65
	v_max3_f32 v153, v153, v34, v35
	v_max3_f32 v153, v153, v36, v37
	v_max3_f32 v153, v153, v38, v39
	v_max3_f32 v153, v153, v40, v41
	v_max3_f32 v153, v153, v42, v43
	v_max3_f32 v153, v153, v44, v45
	v_max3_f32 v153, v153, v46, v47
	v_max3_f32 v153, v153, v48, v49
	v_mov_b32_e32 v162, v153
	s_nop 1
	v_permlane32_swap_b32_e32 v162, v153
	s_nop 1
	v_max_f32_e32 v153, v153, v162
	v_cmp_lt_f32_e32 vcc, s98, v153
	s_cbranch_vccz .LBB0_891
	v_max_f32_e32 v162, s99, v153
	v_sub_f32_e32 v153, 0, v162
	v_min_f32_e32 v153, 0, v153
	v_exp_f32_e32 v153, v153
	v_sub_f32_e32 v206, v206, v162
	v_add_f32_e32 v151, v151, v162
	v_mov_b32_e32 v207, v206
	v_mov_b32_e32 v208, v206
	v_mov_b32_e32 v209, v206
	v_mov_b32_e32 v210, v206
	v_mov_b32_e32 v211, v206
	v_mov_b32_e32 v212, v206
	v_mov_b32_e32 v213, v206
	v_mov_b32_e32 v214, v206
	v_mov_b32_e32 v215, v206
	v_mov_b32_e32 v216, v206
	v_mov_b32_e32 v217, v206
	v_mov_b32_e32 v218, v206
	v_mov_b32_e32 v219, v206
	v_mov_b32_e32 v220, v206
	v_mov_b32_e32 v221, v206
	v_mul_f32_e32 v0, v0, v153
	v_mul_f32_e32 v32, v32, v153
	v_mul_f32_e32 v33, v33, v153
	v_mul_f32_e32 v30, v30, v153
	v_mul_f32_e32 v31, v31, v153
	v_mul_f32_e32 v28, v28, v153
	v_mul_f32_e32 v29, v29, v153
	v_mul_f32_e32 v26, v26, v153
	v_mul_f32_e32 v27, v27, v153
	v_mul_f32_e32 v24, v24, v153
	v_mul_f32_e32 v25, v25, v153
	v_mul_f32_e32 v22, v22, v153
	v_mul_f32_e32 v23, v23, v153
	v_mul_f32_e32 v20, v20, v153
	v_mul_f32_e32 v21, v21, v153
	v_mul_f32_e32 v18, v18, v153
	v_mul_f32_e32 v19, v19, v153
	v_mul_f32_e32 v16, v16, v153
	v_mul_f32_e32 v17, v17, v153
	v_mul_f32_e32 v14, v14, v153
	v_mul_f32_e32 v15, v15, v153
	v_mul_f32_e32 v12, v12, v153
	v_mul_f32_e32 v13, v13, v153
	v_mul_f32_e32 v10, v10, v153
	v_mul_f32_e32 v11, v11, v153
	v_mul_f32_e32 v8, v8, v153
	v_mul_f32_e32 v9, v9, v153
	v_mul_f32_e32 v6, v6, v153
	v_mul_f32_e32 v7, v7, v153
	v_mul_f32_e32 v4, v4, v153
	v_mul_f32_e32 v5, v5, v153
	v_mul_f32_e32 v2, v2, v153
	v_mul_f32_e32 v3, v3, v153
	v_sub_f32_e32 v50, v50, v162
	v_sub_f32_e32 v51, v51, v162
	v_sub_f32_e32 v52, v52, v162
	v_sub_f32_e32 v53, v53, v162
	v_sub_f32_e32 v54, v54, v162
	v_sub_f32_e32 v55, v55, v162
	v_sub_f32_e32 v56, v56, v162
	v_sub_f32_e32 v57, v57, v162
	v_sub_f32_e32 v58, v58, v162
	v_sub_f32_e32 v59, v59, v162
	v_sub_f32_e32 v60, v60, v162
	v_sub_f32_e32 v61, v61, v162
	v_sub_f32_e32 v62, v62, v162
	v_sub_f32_e32 v63, v63, v162
	v_sub_f32_e32 v64, v64, v162
	v_sub_f32_e32 v65, v65, v162
	v_sub_f32_e32 v34, v34, v162
	v_sub_f32_e32 v35, v35, v162
	v_sub_f32_e32 v36, v36, v162
	v_sub_f32_e32 v37, v37, v162
	v_sub_f32_e32 v38, v38, v162
	v_sub_f32_e32 v39, v39, v162
	v_sub_f32_e32 v40, v40, v162
	v_sub_f32_e32 v41, v41, v162
	v_sub_f32_e32 v42, v42, v162
	v_sub_f32_e32 v43, v43, v162
	v_sub_f32_e32 v44, v44, v162
	v_sub_f32_e32 v45, v45, v162
	v_sub_f32_e32 v46, v46, v162
	v_sub_f32_e32 v47, v47, v162
	v_sub_f32_e32 v48, v48, v162
	v_sub_f32_e32 v49, v49, v162
	s_mov_b32 s98, 0x41000000
	s_mov_b32 s99, 0
.LBB0_891:
	v_exp_f32_e32 v50, v50
	v_exp_f32_e32 v51, v51
	v_exp_f32_e32 v52, v52
	v_exp_f32_e32 v53, v53
	v_exp_f32_e32 v54, v54
	v_exp_f32_e32 v55, v55
	v_exp_f32_e32 v56, v56
	v_exp_f32_e32 v57, v57
	v_cvt_pk_bf16_f32 v162, v50, v51
	v_cvt_pk_bf16_f32 v163, v52, v53
	v_cvt_pk_bf16_f32 v164, v54, v55
	v_cvt_pk_bf16_f32 v165, v56, v57
	v_exp_f32_e32 v58, v58
	v_exp_f32_e32 v59, v59
	s_waitcnt lgkmcnt(0)
	v_mfma_f32_32x32x16_bf16 v[2:17], v[126:129], v[162:165], v[2:17]
	v_mfma_f32_32x32x16_bf16 v[18:33], v[122:125], v[162:165], v[18:33]
	v_exp_f32_e32 v60, v60
	v_exp_f32_e32 v61, v61
	v_exp_f32_e32 v62, v62
	v_exp_f32_e32 v63, v63
	v_exp_f32_e32 v64, v64
	v_exp_f32_e32 v65, v65
	v_cvt_pk_bf16_f32 v174, v58, v59
	v_cvt_pk_bf16_f32 v175, v60, v61
	v_cvt_pk_bf16_f32 v176, v62, v63
	v_cvt_pk_bf16_f32 v177, v64, v65
	v_exp_f32_e32 v34, v34
	v_exp_f32_e32 v35, v35
	v_mfma_f32_32x32x16_bf16 v[2:17], v[114:117], v[174:177], v[2:17]
	v_mfma_f32_32x32x16_bf16 v[18:33], v[118:121], v[174:177], v[18:33]
	v_exp_f32_e32 v36, v36
	v_exp_f32_e32 v37, v37
	v_exp_f32_e32 v38, v38
	v_exp_f32_e32 v39, v39
	v_exp_f32_e32 v40, v40
	v_exp_f32_e32 v41, v41
	v_cvt_pk_bf16_f32 v178, v34, v35
	v_cvt_pk_bf16_f32 v179, v36, v37
	v_cvt_pk_bf16_f32 v180, v38, v39
	v_cvt_pk_bf16_f32 v181, v40, v41
	v_exp_f32_e32 v42, v42
	v_exp_f32_e32 v43, v43
	v_mfma_f32_32x32x16_bf16 v[2:17], v[110:113], v[178:181], v[2:17]
	v_mfma_f32_32x32x16_bf16 v[18:33], v[106:109], v[178:181], v[18:33]
	v_exp_f32_e32 v44, v44
	v_exp_f32_e32 v45, v45
	v_exp_f32_e32 v46, v46
	v_exp_f32_e32 v47, v47
	v_exp_f32_e32 v48, v48
	v_exp_f32_e32 v49, v49
	v_cvt_pk_bf16_f32 v182, v42, v43
	v_cvt_pk_bf16_f32 v183, v44, v45
	v_cvt_pk_bf16_f32 v184, v46, v47
	v_cvt_pk_bf16_f32 v185, v48, v49
	s_nop 1
	v_mfma_f32_32x32x16_bf16 v[2:17], v[102:105], v[182:185], v[2:17]
	v_mfma_f32_32x32x16_bf16 v[18:33], v[98:101], v[182:185], v[18:33]
	s_andn2_b64 vcc, exec, s[14:15]
	s_cbranch_vccnz .LBB0_882
	ds_write_b128 v171, v[74:77]
	ds_write2_b64 v149, v[90:91], v[92:93] offset1:1
	s_branch .LBB0_882
